# v059 plus cmp2 tile: importance-partial fold loop (2-3 serial iterations with two dependent LDS round trips each) rewritten as straight-line code with all reads issued up front, same sums
# speedup vs baseline: 1.0047x; 1.0012x over previous
; #define LAS __attribute__((address_space(3)))
; DI void cmpwin_unit(const Params& P, lptr L, int u, int tid, int lane, int wid) {
;     ...
;                 if (jt > 0) {
;                     const LAS float* tp_ = (const LAS float*)(L + AL_TMP) + (cur_ ^ 1) * (8 * 17 * 32);
;                     for (int e = tid; e < 2 * 17 * 32; e += 512) { const int q32 = e & 31, jl = (e >> 5) % 17, qh = e / (17 * 32);
;                         const float a = (tp_[((qh * 4 + 0) * 17 + jl) * 32 + q32] + tp_[((qh * 4 + 1) * 17 + jl) * 32 + q32]) + (tp_[((qh * 4 + 2) * 17 + jl) * 32 + q32] + tp_[((qh * 4 + 3) * 17 + jl) * 32 + q32]);
;                         psl[((n0 - 64) / 4 + jl) * PSL_P + qh * 32 + q32] += a; }
;                 }
.LBB0_552:
	v_lshlrev_b32_e32 v254, 2, v122
	v_lshl_add_u32 v233, v182, 7, v79
	ds_read_b32 v228, v233
	ds_read_b32 v229, v233 offset:2176
	ds_read_b32 v230, v233 offset:4352
	ds_read_b32 v231, v233 offset:6528
	v_add_u32_e32 v234, s2, v182
	v_mul_lo_u32 v234, v234, s6
	v_add_u32_e32 v234, v234, v254
	ds_read_b32 v255, v234 offset:37888
	v_cmp_gt_u32_e32 vcc, 32, v194
	v_add_u32_e32 v240, 16, v182
	v_add_u32_e32 v241, -1, v182
	v_cndmask_b32_e32 v240, v241, v240, vcc
	v_cndmask_b32_e32 v241, v212, v1, vcc
	v_add_u32_e32 v242, v240, v241
	v_lshl_add_u32 v242, v242, 7, v79
	ds_read_b32 v235, v242
	ds_read_b32 v236, v242 offset:2176
	ds_read_b32 v237, v242 offset:4352
	ds_read_b32 v238, v242 offset:6528
	v_add_u32_e32 v243, s2, v240
	v_mul_lo_u32 v243, v243, s6
	v_cndmask_b32_e32 v241, v213, v1, vcc
	v_add3_u32 v243, v243, v241, v254
	ds_read_b32 v239, v243 offset:37888
	v_cmp_gt_u32_e32 vcc, 64, v194
	s_cbranch_vccz .Lfold_w17
	v_add_u32_e32 v252, 15, v182
	v_add_u32_e32 v253, 0x44, v252
	v_lshl_add_u32 v253, v253, 7, v79
	ds_read_b32 v244, v253
	ds_read_b32 v245, v253 offset:2176
	ds_read_b32 v246, v253 offset:4352
	ds_read_b32 v247, v253 offset:6528
	v_add_u32_e32 v252, s2, v252
	v_mul_lo_u32 v252, v252, s6
	v_add3_u32 v252, v252, v213, v254
	ds_read_b32 v248, v252 offset:37888
	s_waitcnt lgkmcnt(0)
	v_add_f32_e32 v244, v244, v245
	v_add_f32_e32 v246, v246, v247
	v_add_f32_e32 v244, v244, v246
	v_add_f32_e32 v244, v248, v244
	ds_write_b32 v252, v244 offset:37888
.Lfold_w17:
	s_waitcnt lgkmcnt(0)
	v_add_f32_e32 v228, v228, v229
	v_add_f32_e32 v230, v230, v231
	v_add_f32_e32 v228, v228, v230
	v_add_f32_e32 v228, v255, v228
	ds_write_b32 v234, v228 offset:37888
	v_add_f32_e32 v235, v235, v236
	v_add_f32_e32 v237, v237, v238
	v_add_f32_e32 v235, v235, v237
	v_add_f32_e32 v235, v239, v235
	ds_write_b32 v243, v235 offset:37888
